# st7 GEMM K-loop: LDS-DMA issues interleaved into first MFMA group, ds_reads issued right after barrier
# speedup vs baseline: 1.0019x; 1.0019x over previous
.LBB0_702:
	s_add_i32 s1, s0, 0x10000
	s_and_b32 s14, s1, 0x10000
	s_and_b32 s0, s0, 0x10000
	s_add_i32 s0, s0, 16
	s_waitcnt vmcnt(0)
	s_barrier
	v_add_u32_e32 v133, s0, v151
	v_add_u32_e32 v168, v133, v166
	ds_read_b128 v[178:181], v168
	ds_read_b128 v[202:205], v168 offset:4096
	ds_read_b128 v[206:209], v168 offset:8192
	ds_read_b128 v[210:213], v168 offset:12288
	v_add_u32_e32 v168, s0, v155
	v_add_u32_e32 v177, v168, v166
	ds_read_b128 v[214:217], v177 offset:32768
	ds_read_b128 v[218:221], v177 offset:36864
	v_add_u32_e32 v190, s14, v161
	v_lshl_add_u64 v[222:223], v[148:149], 0, s[2:3]
	v_readfirstlane_b32 s14, v190
	s_mov_b32 m0, s14
	s_add_i32 s15, s14, 0x2000
	global_load_lds_dwordx4 v[222:223], off
	v_lshl_add_u64 v[222:223], v[146:147], 0, s[2:3]
	s_mov_b32 m0, s15
	s_add_i32 s15, s14, 0x4000
	global_load_lds_dwordx4 v[222:223], off
	s_waitcnt lgkmcnt(1)
	v_mfma_f32_32x32x16_bf16 v[112:127], v[214:217], v[178:181], v[112:127]
	v_lshl_add_u64 v[222:223], v[144:145], 0, s[2:3]
	s_mov_b32 m0, s15
	s_add_i32 s15, s14, 0x6000
	global_load_lds_dwordx4 v[222:223], off
	v_add_u32_e32 v177, v133, v167
	v_mfma_f32_32x32x16_bf16 v[80:95], v[214:217], v[202:205], v[80:95]
	v_lshl_add_u64 v[222:223], v[142:143], 0, s[2:3]
	s_mov_b32 m0, s15
	s_add_i32 s15, s14, 0x8000
	global_load_lds_dwordx4 v[222:223], off
	v_mfma_f32_32x32x16_bf16 v[48:63], v[214:217], v[206:209], v[48:63]
	v_lshl_add_u64 v[222:223], v[140:141], 0, s[2:3]
	s_mov_b32 m0, s15
	s_add_i32 s15, s14, 0xa000
	global_load_lds_dwordx4 v[222:223], off
	v_mfma_f32_32x32x16_bf16 v[16:31], v[214:217], v[210:213], v[16:31]
	v_lshl_add_u64 v[222:223], v[138:139], 0, s[2:3]
	s_mov_b32 m0, s15
	s_add_i32 s15, s14, 0xc000
	global_load_lds_dwordx4 v[222:223], off
	s_waitcnt lgkmcnt(0)
	v_mfma_f32_32x32x16_bf16 v[96:111], v[218:221], v[178:181], v[96:111]
	v_lshl_add_u64 v[222:223], v[136:137], 0, s[2:3]
	s_mov_b32 m0, s15
	s_add_i32 s15, s14, 0xe000
	global_load_lds_dwordx4 v[222:223], off
	v_mfma_f32_32x32x16_bf16 v[64:79], v[218:221], v[202:205], v[64:79]
	v_lshl_add_u64 v[222:223], v[134:135], 0, s[2:3]
	s_mov_b32 m0, s15
	s_nop 0
	global_load_lds_dwordx4 v[222:223], off
	s_add_u32 s2, s2, 0x80
	s_addc_u32 s3, s3, 0
	s_cmpk_eq_i32 s2, 0x780
	s_mov_b32 s0, s1
	v_mfma_f32_32x32x16_bf16 v[32:47], v[218:221], v[206:209], v[32:47]
	v_mfma_f32_32x32x16_bf16 v[0:15], v[218:221], v[210:213], v[0:15]
	ds_read_b128 v[178:181], v177
	ds_read_b128 v[202:205], v177 offset:4096
	ds_read_b128 v[206:209], v177 offset:8192
	ds_read_b128 v[210:213], v177 offset:12288
	v_add_u32_e32 v177, v168, v167
	ds_read_b128 v[214:217], v177 offset:32768
	ds_read_b128 v[218:221], v177 offset:36864
	v_add_u32_e32 v177, v133, v170
	v_add_u32_e32 v133, v133, v171
	s_waitcnt lgkmcnt(1)
	v_mfma_f32_32x32x16_bf16 v[112:127], v[214:217], v[178:181], v[112:127]
	v_mfma_f32_32x32x16_bf16 v[80:95], v[214:217], v[202:205], v[80:95]
	v_mfma_f32_32x32x16_bf16 v[48:63], v[214:217], v[206:209], v[48:63]
	v_mfma_f32_32x32x16_bf16 v[16:31], v[214:217], v[210:213], v[16:31]
	s_waitcnt lgkmcnt(0)
	v_mfma_f32_32x32x16_bf16 v[96:111], v[218:221], v[178:181], v[96:111]
	v_mfma_f32_32x32x16_bf16 v[64:79], v[218:221], v[202:205], v[64:79]
	v_mfma_f32_32x32x16_bf16 v[32:47], v[218:221], v[206:209], v[32:47]
	v_mfma_f32_32x32x16_bf16 v[0:15], v[218:221], v[210:213], v[0:15]
	ds_read_b128 v[178:181], v177
	ds_read_b128 v[202:205], v177 offset:4096
	ds_read_b128 v[206:209], v177 offset:8192
	ds_read_b128 v[210:213], v177 offset:12288
	v_add_u32_e32 v177, v168, v170
	ds_read_b128 v[214:217], v177 offset:32768
	ds_read_b128 v[218:221], v177 offset:36864
	s_waitcnt lgkmcnt(1)
	v_mfma_f32_32x32x16_bf16 v[112:127], v[214:217], v[178:181], v[112:127]
	v_mfma_f32_32x32x16_bf16 v[80:95], v[214:217], v[202:205], v[80:95]
	v_mfma_f32_32x32x16_bf16 v[48:63], v[214:217], v[206:209], v[48:63]
	v_mfma_f32_32x32x16_bf16 v[16:31], v[214:217], v[210:213], v[16:31]
	s_waitcnt lgkmcnt(0)
	v_mfma_f32_32x32x16_bf16 v[96:111], v[218:221], v[178:181], v[96:111]
	v_mfma_f32_32x32x16_bf16 v[64:79], v[218:221], v[202:205], v[64:79]
	v_mfma_f32_32x32x16_bf16 v[32:47], v[218:221], v[206:209], v[32:47]
	v_mfma_f32_32x32x16_bf16 v[0:15], v[218:221], v[210:213], v[0:15]
	ds_read_b128 v[178:181], v133
	ds_read_b128 v[202:205], v133 offset:4096
	ds_read_b128 v[206:209], v133 offset:8192
	ds_read_b128 v[210:213], v133 offset:12288
	v_add_u32_e32 v133, v168, v171
	ds_read_b128 v[214:217], v133 offset:32768
	ds_read_b128 v[218:221], v133 offset:36864
	s_waitcnt lgkmcnt(1)
	v_mfma_f32_32x32x16_bf16 v[112:127], v[214:217], v[178:181], v[112:127]
	v_mfma_f32_32x32x16_bf16 v[80:95], v[214:217], v[202:205], v[80:95]
	v_mfma_f32_32x32x16_bf16 v[48:63], v[214:217], v[206:209], v[48:63]
	v_mfma_f32_32x32x16_bf16 v[16:31], v[214:217], v[210:213], v[16:31]
	s_waitcnt lgkmcnt(0)
	v_mfma_f32_32x32x16_bf16 v[96:111], v[218:221], v[178:181], v[96:111]
	v_mfma_f32_32x32x16_bf16 v[64:79], v[218:221], v[202:205], v[64:79]
	v_mfma_f32_32x32x16_bf16 v[32:47], v[218:221], v[206:209], v[32:47]
	v_mfma_f32_32x32x16_bf16 v[0:15], v[218:221], v[210:213], v[0:15]
	s_cbranch_scc0 .LBB0_702
	s_waitcnt vmcnt(0)
	s_barrier
	v_mov_b32_e32 v133, 0x358637bd
	s_and_saveexec_b64 s[2:3], s[6:7]
	s_cbranch_execz .LBB0_705
	v_add_u32_e32 v134, s17, v150
	v_ashrrev_i32_e32 v135, 31, v134
	v_lshlrev_b64 v[134:135], 6, v[134:135]
	v_lshl_add_u64 v[146:147], s[10:11], 0, v[134:135]
	global_load_dwordx4 v[134:137], v[146:147], off
	global_load_dwordx4 v[138:141], v[146:147], off offset:16
	global_load_dwordx4 v[142:145], v[146:147], off offset:32
	s_nop 0
	global_load_dwordx4 v[146:149], v[146:147], off offset:48
	s_waitcnt vmcnt(3)
	v_mov_b32_e32 v178, v135
	v_mov_b32_e32 v179, v136
	v_mov_b32_e32 v135, v137
	v_pk_add_f32 v[134:135], v[178:179], v[134:135]
	s_waitcnt vmcnt(2)
	v_mov_b32_e32 v180, v139
	v_mov_b32_e32 v181, v140
	v_mov_b32_e32 v139, v141
	v_add_f32_e32 v133, 0, v134
	v_pk_add_f32 v[136:137], v[180:181], v[138:139]
	v_add_f32_e32 v133, v133, v135
	s_waitcnt vmcnt(1)
	v_mov_b32_e32 v182, v143
	v_mov_b32_e32 v183, v144
	v_mov_b32_e32 v143, v145
	v_add_f32_e32 v133, v133, v136
	v_pk_add_f32 v[138:139], v[182:183], v[142:143]
	v_add_f32_e32 v133, v133, v137
	s_waitcnt vmcnt(0)
	v_mov_b32_e32 v202, v147
	v_mov_b32_e32 v203, v148
	v_mov_b32_e32 v147, v149
	v_add_f32_e32 v133, v133, v138
	v_add_f32_e32 v133, v133, v139
	v_pk_add_f32 v[134:135], v[202:203], v[146:147]
	s_nop 0
	v_add_f32_e32 v133, v133, v134
	v_add_f32_e32 v133, v133, v135
	v_fmamk_f32 v133, v133, 0x3a800000, v187
